# differential attention P*V: V fragments read in the S^T accumulator's key order (one address bit + read immediates changed), the 8 v_permlane32_swap per tile that re-ordered the bf16 P fragment are go
# speedup vs baseline: 1.0104x; 1.0104x over previous
.LBB0_422:
	s_lshl_b32 s0, s39, 10
	s_and_b32 s6, s0, 0x800000
	s_lshl_b32 s0, s43, 1
	s_and_b32 s66, s0, 0x300
	s_lshl_b32 s0, s64, 11
	s_lshl_b32 s1, s64, 4
	s_and_b32 s0, s0, 0x2000
	s_and_b32 s1, s1, 0xffffff80
	s_add_i32 s1, s0, s1
	v_or_b32_e32 v171, s1, v170
	v_or_b32_e32 v0, v171, v169
	v_ashrrev_i32_e32 v1, 31, v0
	s_lshl_b32 s1, s64, 7
	v_lshlrev_b64 v[0:1], 10, v[0:1]
	s_and_b32 s65, s1, 0x180
	v_lshl_add_u64 v[0:1], s[86:87], 0, v[0:1]
	s_lshl_b32 s4, s65, 1
	s_mov_b32 s5, s7
	v_lshl_add_u64 v[0:1], v[0:1], 0, s[4:5]
	s_lshl_b32 s5, s0, 10
	s_add_u32 s0, s33, s5
	s_addc_u32 s1, s34, 0
	s_add_u32 s0, s0, s4
	v_mov_b32_e32 v174, v168
	v_lshl_add_u64 v[0:1], v[160:161], 1, v[0:1]
	s_addc_u32 s1, s1, 0
	v_lshl_add_u64 v[0:1], v[0:1], 0, v[162:163]
	v_ashrrev_i32_e32 v16, 4, v174
	s_add_u32 s5, s35, s5
	v_lshlrev_b32_e32 v20, 3, v174
	v_add_u32_e32 v18, 32, v16
	s_addc_u32 s16, s38, 0
	global_load_dwordx4 v[124:127], v[0:1], off
	global_load_dwordx4 v[120:123], v[0:1], off offset:32
	global_load_dwordx4 v[116:119], v[0:1], off offset:64
	global_load_dwordx4 v[112:115], v[0:1], off offset:96
	v_and_b32_e32 v0, 0x78, v20
	v_ashrrev_i32_e32 v17, 31, v16
	v_ashrrev_i32_e32 v19, 31, v18
	s_add_u32 s4, s5, s4
	v_lshlrev_b32_e32 v21, 1, v0
	v_lshlrev_b64 v[48:49], 10, v[16:17]
	v_lshlrev_b64 v[12:13], 10, v[18:19]
	s_addc_u32 s5, s16, 0
	v_or_b32_e32 v50, v48, v21
	v_mov_b32_e32 v51, v49
	v_or_b32_e32 v12, v12, v21
	v_lshl_add_u64 v[0:1], s[4:5], 0, v[50:51]
	v_lshl_add_u64 v[4:5], s[4:5], 0, v[12:13]
	s_barrier
	global_load_dwordx4 v[0:3], v[0:1], off
	s_nop 0
	global_load_dwordx4 v[4:7], v[4:5], off
	v_lshl_add_u64 v[8:9], s[0:1], 0, v[50:51]
	global_load_dwordx4 v[8:11], v[8:9], off
	v_lshl_add_u64 v[12:13], s[0:1], 0, v[12:13]
	global_load_dwordx4 v[12:15], v[12:13], off
	v_and_b32_e32 v22, 0xfffff0, v16
	v_lshlrev_b32_e32 v23, 1, v16
	v_lshrrev_b32_e32 v24, 1, v16
	v_and_b32_e32 v25, 3, v16
	v_and_or_b32 v22, v23, 8, v22
	v_and_or_b32 v23, v24, 4, v25
	v_and_b32_e32 v24, 0xfffff0, v18
	v_lshlrev_b32_e32 v25, 1, v18
	v_and_b32_e32 v17, 0x70, v174
	v_bfe_u32 v20, v20, 5, 2
	v_lshlrev_b32_e32 v16, 8, v16
	v_lshrrev_b32_e32 v22, 1, v22
	v_and_or_b32 v24, v25, 8, v24
	v_bitop3_b32 v183, v21, v16, v17 bitop3:0xde
	v_or_b32_e32 v16, v22, v20
	v_lshrrev_b32_e32 v22, 1, v24
	v_lshlrev_b32_e32 v23, 6, v23
	v_and_b32_e32 v26, 48, v21
	v_lshlrev_b32_e32 v16, 9, v16
	v_or_b32_e32 v20, v22, v20
	v_or3_b32 v184, v16, v23, v26
	v_lshlrev_b32_e32 v16, 9, v20
	v_bfe_u32 v172, v174, 5, 1
	v_ashrrev_i32_e32 v175, 8, v174
	v_lshlrev_b32_e32 v52, 4, v174
	v_or3_b32 v186, v16, v23, v26
	v_add_u32_e32 v84, 16, v184
	v_and_b32_e32 v173, 31, v174
	v_lshlrev_b32_e32 v19, 7, v175
	v_add_u32_e32 v24, 16, v183
	v_add_u32_e32 v85, 16, v186
	s_waitcnt vmcnt(0)
	v_lshlrev_b32_e32 v176, 4, v172
	v_lshlrev_b32_e32 v190, 8, v173
	v_and_b32_e32 v86, 63, v174
	v_lshl_add_u64 v[60:61], v[50:51], 0, s[14:15]
	v_lshl_add_u64 v[64:65], v[50:51], 0, s[36:37]
	v_lshl_add_u64 v[56:57], s[4:5], 0, v[64:65]
	v_lshl_add_u64 v[64:65], s[0:1], 0, v[64:65]
	s_cmp_lg_u32 16, -1
	s_cselect_b32 s16, 16, 0
	s_mov_b32 s17, s7
	s_mov_b32 s18, s7
	s_mov_b32 s19, s7
	s_mov_b32 s20, s7
	s_waitcnt vmcnt(3)
	ds_write_b128 v84, v[0:3]
	s_waitcnt vmcnt(2)
	ds_write_b128 v85, v[4:7]
	s_waitcnt vmcnt(1)
	ds_write_b128 v24, v[8:11] offset:49152
	v_and_b32_e32 v8, 0x70, v52
	v_lshlrev_b32_e32 v0, 8, v18
	v_bitop3_b32 v182, v176, v8, v19 bitop3:0x36
	v_bitop3_b32 v188, v21, v0, v17 bitop3:0xde
	v_add_u32_e32 v185, v182, v190
	v_add_u32_e32 v0, 16, v188
	v_add_u32_e32 v4, 16, v185
	s_waitcnt vmcnt(0)
	ds_write_b128 v0, v[12:15] offset:49152
	s_waitcnt lgkmcnt(0)
	s_barrier
	ds_read_b128 v[0:3], v4 offset:49152
	ds_read_b128 v[4:7], v4 offset:57344
	v_or_b32_e32 v9, v176, v19
	v_bitop3_b32 v187, v9, v8, 32 bitop3:0x36
	v_add_u32_e32 v189, v187, v190
	s_waitcnt lgkmcnt(0)
	v_mfma_f32_32x32x16_bf16 v[16:31], v[4:7], v[124:127], 0
	v_add_u32_e32 v4, 16, v189
	v_bitop3_b32 v193, v9, v8, s3 bitop3:0x36
	v_bitop3_b32 v191, v9, v8, 64 bitop3:0x36
	v_add_u32_e32 v194, v193, v190
	v_add_u32_e32 v192, v191, v190
	v_add_u32_e32 v8, 16, v194
	v_and_b32_e32 v5, 0x3fffffc0, v174
	v_mfma_f32_32x32x16_bf16 v[32:47], v[0:3], v[124:127], 0
	ds_read_b128 v[0:3], v4 offset:49152
	v_and_b32_e32 v11, 0xc0, v52
	v_add_u32_e32 v13, 16, v192
	ds_read_b128 v[52:55], v8 offset:57344
	v_lshl_add_u32 v177, v5, 2, s50
	ds_read_b128 v[4:7], v4 offset:57344
	v_lshlrev_b32_e32 v10, 3, v86
	s_waitcnt lgkmcnt(2)
	v_mfma_f32_32x32x16_bf16 v[32:47], v[0:3], v[120:123], v[32:47]
	v_lshlrev_b32_e32 v0, 1, v174
	v_and_b32_e32 v12, 32, v0
	ds_read_b128 v[0:3], v13 offset:49152
	v_and_or_b32 v11, v10, 24, v11
	s_mov_b32 s21, s7
	s_mov_b32 s22, s7
	s_mov_b32 s23, s7
	s_waitcnt lgkmcnt(0)
	v_mfma_f32_32x32x16_bf16 v[32:47], v[0:3], v[116:119], v[32:47]
	ds_read_b128 v[0:3], v8 offset:49152
	s_mov_b32 s24, s7
	s_mov_b32 s25, s7
	s_mov_b32 s26, s7
	s_mov_b32 s27, s7
	s_mov_b32 s28, s7
	s_mov_b32 s29, s7
	v_mfma_f32_32x32x16_bf16 v[16:31], v[4:7], v[120:123], v[16:31]
	v_and_b32_e32 v4, 0x100, v10
	v_lshlrev_b32_e32 v4, 3, v4
	v_or3_b32 v178, v11, v12, v4
	ds_read_b128 v[4:7], v13 offset:57344
	v_add_u32_e32 v181, s16, v178
	s_mov_b32 s16, s7
	s_mov_b32 s30, s7
	s_mov_b32 s31, s7
	s_waitcnt lgkmcnt(0)
	v_mfma_f32_32x32x16_bf16 v[16:31], v[4:7], v[116:119], v[16:31]
	v_lshl_add_u32 v179, v173, 2, v177
	v_mov_b32_e32 v196, 1.0
	v_mov_b32_e32 v180, 0
	v_mfma_f32_32x32x16_bf16 v[32:47], v[0:3], v[112:115], v[32:47]
	v_mov_b64_e32 v[0:1], s[16:17]
	v_mov_b64_e32 v[14:15], s[30:31]
	v_mov_b64_e32 v[2:3], s[18:19]
	v_mov_b64_e32 v[4:5], s[20:21]
	v_mov_b64_e32 v[6:7], s[22:23]
	v_mov_b64_e32 v[8:9], s[24:25]
	v_mov_b64_e32 v[10:11], s[26:27]
	v_mfma_f32_32x32x16_bf16 v[16:31], v[52:55], v[112:115], v[16:31]
	s_nop 3
	v_max_f32_e32 v52, v33, v33
	v_max_f32_e32 v53, v32, v32
	v_max_f32_e32 v52, v53, v52
	v_max3_f32 v52, v52, v34, v35
	v_max3_f32 v52, v52, v36, v37
	v_max3_f32 v52, v52, v38, v39
	v_max3_f32 v52, v52, v40, v41
	v_max3_f32 v52, v52, v42, v43
	v_max3_f32 v52, v52, v44, v45
	v_max3_f32 v66, v52, v46, v47
	v_lshl_add_u64 v[52:53], s[4:5], 0, v[60:61]
	v_lshl_add_u64 v[60:61], s[0:1], 0, v[60:61]
	global_load_dwordx4 v[52:55], v[52:53], off
	s_nop 0
	global_load_dwordx4 v[56:59], v[56:57], off
	v_mov_b64_e32 v[12:13], s[28:29]
	global_load_dwordx4 v[60:63], v[60:61], off
	s_mov_b32 s19, 1
	global_load_dwordx4 v[80:83], v[64:65], off
	v_max3_f32 v64, v66, v16, v17
	v_max3_f32 v64, v64, v18, v19
	v_max3_f32 v64, v64, v20, v21
	v_max3_f32 v64, v64, v22, v23
	v_max3_f32 v64, v64, v24, v25
	v_max3_f32 v64, v64, v26, v27
	v_max3_f32 v64, v64, v28, v29
	v_max3_f32 v70, v64, v30, v31
	v_lshl_add_u64 v[64:65], v[50:51], 0, s[40:41]
	v_lshl_add_u64 v[66:67], s[0:1], 0, v[64:65]
	v_lshl_add_u64 v[50:51], v[50:51], 0, s[44:45]
	v_lshl_add_u64 v[64:65], s[4:5], 0, v[64:65]
	v_lshl_add_u64 v[68:69], s[0:1], 0, v[50:51]
	global_load_dwordx4 v[136:139], v[66:67], off
	global_load_dwordx4 v[128:131], v[68:69], off
	v_lshl_add_u64 v[50:51], s[4:5], 0, v[50:51]
	global_load_dwordx4 v[140:143], v[64:65], off
	global_load_dwordx4 v[132:135], v[50:51], off
	v_mov_b32_e32 v71, v70
	s_nop 1
	v_permlane32_swap_b32_e32 v70, v71
	v_max_f32_e32 v50, v71, v71
	v_max_f32_e32 v51, v70, v70
	v_max_f32_e32 v50, v51, v50
	v_sub_f32_e32 v64, v16, v50
	v_add_u32_e32 v16, s58, v183
	v_sub_f32_e32 v32, v32, v50
	v_sub_f32_e32 v33, v33, v50
	v_sub_f32_e32 v34, v34, v50
	v_sub_f32_e32 v35, v35, v50
	v_sub_f32_e32 v36, v36, v50
	v_sub_f32_e32 v37, v37, v50
	v_sub_f32_e32 v38, v38, v50
	v_sub_f32_e32 v39, v39, v50
	v_sub_f32_e32 v40, v40, v50
	v_sub_f32_e32 v41, v41, v50
	v_sub_f32_e32 v42, v42, v50
	v_sub_f32_e32 v43, v43, v50
	v_sub_f32_e32 v44, v44, v50
	v_sub_f32_e32 v45, v45, v50
	v_sub_f32_e32 v46, v46, v50
	v_sub_f32_e32 v47, v47, v50
	v_sub_f32_e32 v66, v18, v50
	s_waitcnt vmcnt(4)
	s_waitcnt vmcnt(7)
	ds_write_b128 v84, v[52:55] offset:16384
	s_waitcnt vmcnt(6)
	ds_write_b128 v85, v[56:59] offset:16384
	v_and_b32_e32 v18, 15, v174
	s_waitcnt vmcnt(5)
	ds_write_b128 v16, v[60:63]
	v_add_u32_e32 v16, s58, v188
	v_sub_f32_e32 v65, v17, v50
	v_exp_f32_e32 v152, v32
	v_exp_f32_e32 v153, v33
	v_exp_f32_e32 v154, v34
	v_exp_f32_e32 v155, v35
	v_exp_f32_e32 v156, v36
	v_exp_f32_e32 v157, v37
	v_exp_f32_e32 v158, v38
	v_exp_f32_e32 v159, v39
	v_exp_f32_e32 v144, v40
	v_exp_f32_e32 v145, v41
	v_exp_f32_e32 v146, v42
	v_exp_f32_e32 v147, v43
	v_exp_f32_e32 v148, v44
	v_exp_f32_e32 v149, v45
	v_exp_f32_e32 v150, v46
	v_exp_f32_e32 v151, v47
	s_waitcnt vmcnt(4)
	ds_write_b128 v16, v[80:83]
	v_lshl_add_u64 v[16:17], s[6:7], 0, v[48:49]
	v_lshlrev_b32_e32 v18, 4, v18
	v_or3_b32 v16, v16, s66, v18
	v_add_f32_e32 v195, 0, v50
	v_sub_f32_e32 v79, v31, v50
	v_sub_f32_e32 v78, v30, v50
	v_sub_f32_e32 v77, v29, v50
	v_sub_f32_e32 v76, v28, v50
	v_sub_f32_e32 v75, v27, v50
	v_sub_f32_e32 v74, v26, v50
	v_sub_f32_e32 v73, v25, v50
	v_sub_f32_e32 v72, v24, v50
	v_sub_f32_e32 v71, v23, v50
	v_sub_f32_e32 v70, v22, v50
	v_sub_f32_e32 v69, v21, v50
	v_sub_f32_e32 v68, v20, v50
	v_sub_f32_e32 v67, v19, v50
	v_lshl_add_u64 v[166:167], s[12:13], 0, v[16:17]
	v_mov_b64_e32 v[62:63], v[14:15]
	v_mov_b64_e32 v[46:47], v[14:15]
	v_mov_b64_e32 v[30:31], v[14:15]
	v_cmp_gt_u32_e64 s[0:1], 32, v86
	v_mov_b64_e32 v[60:61], v[12:13]
	v_mov_b64_e32 v[58:59], v[10:11]
	v_mov_b64_e32 v[56:57], v[8:9]
	v_mov_b64_e32 v[54:55], v[6:7]
	v_mov_b64_e32 v[52:53], v[4:5]
	v_mov_b64_e32 v[50:51], v[2:3]
	v_mov_b64_e32 v[48:49], v[0:1]
	v_mov_b64_e32 v[44:45], v[12:13]
	v_mov_b64_e32 v[42:43], v[10:11]
	v_mov_b64_e32 v[40:41], v[8:9]
	v_mov_b64_e32 v[38:39], v[6:7]
	v_mov_b64_e32 v[36:37], v[4:5]
	v_mov_b64_e32 v[34:35], v[2:3]
	v_mov_b64_e32 v[32:33], v[0:1]
	v_mov_b64_e32 v[28:29], v[12:13]
	v_mov_b64_e32 v[26:27], v[10:11]
	v_mov_b64_e32 v[24:25], v[8:9]
	v_mov_b64_e32 v[22:23], v[6:7]
	v_mov_b64_e32 v[20:21], v[4:5]
	v_mov_b64_e32 v[18:19], v[2:3]
	v_mov_b64_e32 v[16:17], v[0:1]
	s_mov_b32 s6, 1
	s_mov_b32 s18, 0
	s_waitcnt lgkmcnt(0)
	s_barrier
	v_add_co_u32_e32 v242, vcc, s61, v166
	s_nop 1
	v_addc_co_u32_e32 v243, vcc, -1, v167, vcc
	s_nop 0
	v_readfirstlane_b32 s98, v242
	v_readfirstlane_b32 s99, v243
	s_nop 1
	v_subrev_u32_e32 v242, s98, v242
	v_add_u32_e32 v243, 0x8000, v242
	v_add_u32_e32 v244, 0x1000000, v242
	v_add_u32_e32 v245, 0x1008000, v242
.LBB0_423:
	s_lshl_b32 s16, s19, 14
	s_add_i32 s4, s16, 16
	v_add_u32_e32 v96, s4, v185
	ds_read_b128 v[198:201], v96 offset:49152
	ds_read_b128 v[202:205], v96 offset:57344
	v_xor_b32_e32 v80, 0x80000000, v195
	v_mov_b32_e32 v81, v80
	v_mov_b64_e32 v[82:83], v[80:81]
	v_mov_b64_e32 v[84:85], v[80:81]
	v_mov_b64_e32 v[86:87], v[80:81]
	v_mov_b64_e32 v[88:89], v[80:81]
	v_mov_b64_e32 v[90:91], v[80:81]
	v_mov_b64_e32 v[92:93], v[80:81]
	v_mov_b64_e32 v[94:95], v[80:81]
	v_exp_f32_e32 v221, v64
	v_add_f32_e32 v64, 0, v152
	s_waitcnt lgkmcnt(1)
	v_mfma_f32_32x32x16_bf16 v[96:111], v[198:201], v[124:127], v[80:95]
	v_add_f32_e32 v64, v153, v64
	v_add_f32_e32 v64, v154, v64
	v_add_u32_e32 v197, s4, v189
	v_add_f32_e32 v64, v155, v64
	v_add_f32_e32 v64, v156, v64
	v_add_f32_e32 v64, v157, v64
	v_add_f32_e32 v64, v158, v64
	s_waitcnt lgkmcnt(0)
	v_mfma_f32_32x32x16_bf16 v[80:95], v[202:205], v[124:127], v[80:95]
	ds_read_b128 v[198:201], v197 offset:49152
	ds_read_b128 v[202:205], v197 offset:57344
	v_add_f32_e32 v64, v159, v64
	v_add_f32_e32 v64, v144, v64
	v_add_f32_e32 v64, v145, v64
	v_add_f32_e32 v64, v146, v64
	v_add_u32_e32 v197, s4, v192
	v_add_f32_e32 v64, v147, v64
	s_waitcnt lgkmcnt(1)
	v_mfma_f32_32x32x16_bf16 v[96:111], v[198:201], v[120:123], v[96:111]
	ds_read_b128 v[198:201], v197 offset:49152
	ds_read_b128 v[206:209], v197 offset:57344
	v_add_f32_e32 v64, v148, v64
	v_exp_f32_e32 v222, v65
	v_add_f32_e32 v64, v149, v64
	v_exp_f32_e32 v223, v66
	v_add_f32_e32 v64, v150, v64
	v_exp_f32_e32 v224, v67
	s_waitcnt lgkmcnt(2)
	v_mfma_f32_32x32x16_bf16 v[80:95], v[202:205], v[120:123], v[80:95]
	v_add_f32_e32 v64, v151, v64
	v_add_f32_e32 v64, v221, v64
	v_add_f32_e32 v64, v222, v64
	v_add_f32_e32 v64, v223, v64
	v_exp_f32_e32 v71, v71
	v_add_f32_e32 v64, v224, v64
	v_add_u32_e32 v197, s4, v194
	s_waitcnt lgkmcnt(1)
	v_mfma_f32_32x32x16_bf16 v[96:111], v[198:201], v[116:119], v[96:111]
	v_exp_f32_e32 v199, v68
	v_exp_f32_e32 v200, v69
	v_exp_f32_e32 v201, v70
	v_exp_f32_e32 v225, v72
	v_add_f32_e32 v64, v199, v64
	ds_read_b128 v[202:205], v197 offset:49152
	ds_read_b128 v[210:213], v197 offset:57344
	v_exp_f32_e32 v226, v73
	s_waitcnt lgkmcnt(2)
	v_mfma_f32_32x32x16_bf16 v[80:95], v[206:209], v[116:119], v[80:95]
	v_add_f32_e32 v64, v200, v64
	v_exp_f32_e32 v227, v74
	v_add_f32_e32 v64, v201, v64
	v_exp_f32_e32 v206, v75
	v_add_f32_e32 v64, v71, v64
	v_exp_f32_e32 v207, v76
	v_add_f32_e32 v64, v225, v64
	v_exp_f32_e32 v208, v77
	v_add_f32_e32 v64, v226, v64
	v_exp_f32_e32 v209, v78
	s_waitcnt lgkmcnt(1)
	v_mfma_f32_32x32x16_bf16 v[96:111], v[202:205], v[112:115], v[96:111]
	v_add_f32_e32 v64, v227, v64
	v_exp_f32_e32 v79, v79
	v_add_f32_e32 v64, v206, v64
	v_add_f32_e32 v64, v207, v64
	v_add_f32_e32 v64, v208, v64
	v_add_f32_e32 v64, v209, v64
	v_add_f32_e32 v197, v79, v64
	s_waitcnt lgkmcnt(0)
	v_mfma_f32_32x32x16_bf16 v[80:95], v[210:213], v[112:115], v[80:95]
	v_mov_b32_e32 v198, v197
	v_cvt_pk_bf16_f32 v64, v152, v153
	v_cvt_pk_bf16_f32 v65, v154, v155
	v_cvt_pk_bf16_f32 v66, v156, v157
	v_cvt_pk_bf16_f32 v67, v158, v159
	v_cvt_pk_bf16_f32 v72, v144, v145
	v_cvt_pk_bf16_f32 v73, v146, v147
	v_cvt_pk_bf16_f32 v74, v148, v149
	v_cvt_pk_bf16_f32 v75, v150, v151
	v_cvt_pk_bf16_f32 v68, v221, v222
	v_cvt_pk_bf16_f32 v69, v223, v224
	v_cvt_pk_bf16_f32 v70, v199, v200
	v_cvt_pk_bf16_f32 v71, v201, v71
	v_cvt_pk_bf16_f32 v76, v225, v226
	v_cvt_pk_bf16_f32 v77, v227, v206
	v_cvt_pk_bf16_f32 v78, v207, v208
	v_cvt_pk_bf16_f32 v79, v209, v79
	v_permlane32_swap_b32_e32 v197, v198
	global_load_dwordx4 v[144:147], v244, s[98:99]
	global_load_dwordx4 v[148:151], v245, s[98:99]
	global_load_dwordx4 v[152:155], v242, s[98:99]
	global_load_dwordx4 v[156:159], v243, s[98:99]
	s_add_u32 s98, s98, 0x10000
	s_addc_u32 s99, s99, 0
	v_lshl_add_u32 v199, s18, 14, v181
	ds_read_b64_tr_b16 v[200:201], v199 offset:0
	ds_read_b64_tr_b16 v[202:203], v199 offset:0x100
	ds_read_b64_tr_b16 v[204:205], v199 offset:0x1000
	ds_read_b64_tr_b16 v[206:207], v199 offset:0x1100
	ds_read_b64_tr_b16 v[208:209], v199 offset:0x2000
	ds_read_b64_tr_b16 v[210:211], v199 offset:0x2100
	ds_read_b64_tr_b16 v[222:223], v199 offset:0x3000
	ds_read_b64_tr_b16 v[224:225], v199 offset:0x3100
	s_nop 0
	s_waitcnt lgkmcnt(6)
	v_mfma_f32_32x32x16_bf16 v[0:15], v[64:67], v[200:203], v[0:15]
	v_max_f32_e32 v200, v97, v97
	v_max_f32_e32 v201, v96, v96
	v_max_f32_e32 v200, v201, v200
	v_max3_f32 v200, v200, v98, v99
	v_max3_f32 v200, v200, v100, v101
	v_max3_f32 v200, v200, v102, v103
	v_max3_f32 v200, v200, v104, v105
	s_waitcnt lgkmcnt(4)
	v_mfma_f32_32x32x16_bf16 v[0:15], v[72:75], v[204:207], v[0:15]
	v_max3_f32 v200, v200, v106, v107
	v_max3_f32 v202, v200, v108, v109
	ds_read_b64_tr_b16 v[200:201], v199 offset:0x200
	v_max3_f32 v212, v202, v110, v111
	ds_read_b64_tr_b16 v[202:203], v199 offset:0x300
	ds_read_b64_tr_b16 v[204:205], v199 offset:0x1200
	ds_read_b64_tr_b16 v[206:207], v199 offset:0x1300
	s_waitcnt lgkmcnt(6)
	v_mfma_f32_32x32x16_bf16 v[0:15], v[68:71], v[208:211], v[0:15]
	ds_read_b64_tr_b16 v[208:209], v199 offset:0x2200
	ds_read_b64_tr_b16 v[210:211], v199 offset:0x2300
	ds_read_b64_tr_b16 v[226:227], v199 offset:0x3200
	ds_read_b64_tr_b16 v[228:229], v199 offset:0x3300
	s_waitcnt lgkmcnt(8)
	v_mfma_f32_32x32x16_bf16 v[0:15], v[76:79], v[222:225], v[0:15]
	s_waitcnt lgkmcnt(6)
	v_mfma_f32_32x32x16_bf16 v[48:63], v[64:67], v[200:203], v[48:63]
	v_max3_f32 v212, v212, v80, v81
	v_max3_f32 v200, v212, v82, v83
	ds_read_b64_tr_b16 v[202:203], v199 offset:0x400
	v_max3_f32 v200, v200, v84, v85
	v_max3_f32 v200, v200, v86, v87
	v_max3_f32 v200, v200, v88, v89
	v_max3_f32 v200, v200, v90, v91
	s_waitcnt lgkmcnt(5)
	v_mfma_f32_32x32x16_bf16 v[48:63], v[72:75], v[204:207], v[48:63]
	ds_read_b64_tr_b16 v[204:205], v199 offset:0x500
	ds_read_b64_tr_b16 v[206:207], v199 offset:0x1400
	v_max3_f32 v200, v200, v92, v93
	v_max3_f32 v200, v200, v94, v95
	v_mov_b32_e32 v201, v200
	s_nop 1
	v_permlane32_swap_b32_e32 v200, v201
	s_waitcnt lgkmcnt(5)
	v_mfma_f32_32x32x16_bf16 v[48:63], v[68:71], v[208:211], v[48:63]
	ds_read_b64_tr_b16 v[208:209], v199 offset:0x1500
	ds_read_b64_tr_b16 v[210:211], v199 offset:0x2400
	ds_read_b64_tr_b16 v[212:213], v199 offset:0x2500
	ds_read_b64_tr_b16 v[222:223], v199 offset:0x3400
	ds_read_b64_tr_b16 v[224:225], v199 offset:0x3500
	v_max_f32_e32 v201, v201, v201
	s_waitcnt lgkmcnt(8)
	v_mfma_f32_32x32x16_bf16 v[48:63], v[76:79], v[226:229], v[48:63]
	v_max_f32_e32 v200, v200, v200
	v_max_f32_e32 v200, v200, v201
	s_waitcnt lgkmcnt(6)
	v_mfma_f32_32x32x16_bf16 v[32:47], v[64:67], v[202:205], v[32:47]
	v_cmp_ge_f32_e32 vcc, s63, v200
	s_cmp_eq_u64 vcc, exec
	s_waitcnt lgkmcnt(4)
	v_mfma_f32_32x32x16_bf16 v[32:47], v[72:75], v[206:209], v[32:47]
	s_waitcnt lgkmcnt(2)
	v_mfma_f32_32x32x16_bf16 v[32:47], v[68:71], v[210:213], v[32:47]
	s_waitcnt lgkmcnt(0)
	v_mfma_f32_32x32x16_bf16 v[32:47], v[76:79], v[222:225], v[32:47]
	s_cbranch_scc0 .LBB0_438
	v_mov_b32_e32 v200, 1.0
.LBB0_425:
	ds_read_b64_tr_b16 v[202:203], v199 offset:0x600
	ds_read_b64_tr_b16 v[204:205], v199 offset:0x700
	ds_read_b64_tr_b16 v[206:207], v199 offset:0x1600
	ds_read_b64_tr_b16 v[208:209], v199 offset:0x1700
	ds_read_b64_tr_b16 v[210:211], v199 offset:0x2600
	ds_read_b64_tr_b16 v[212:213], v199 offset:0x2700
	ds_read_b64_tr_b16 v[222:223], v199 offset:0x3600
	ds_read_b64_tr_b16 v[224:225], v199 offset:0x3700
	s_add_i32 s4, s19, 1
	s_cmp_lg_u32 s19, 2
	s_cselect_b32 s18, s4, 0
	s_waitcnt lgkmcnt(6)
	v_mfma_f32_32x32x16_bf16 v[16:31], v[64:67], v[202:205], v[16:31]
	s_lshl_b32 s4, s18, 14
	s_add_i32 s17, s4, 16
	v_add_u32_e32 v64, s17, v184
	s_waitcnt vmcnt(4)
	s_waitcnt vmcnt(4)
	ds_write_b128 v64, v[132:135]
	v_add_u32_e32 v64, s17, v186
	ds_write_b128 v64, v[140:143]
	s_waitcnt lgkmcnt(6)
	v_mfma_f32_32x32x16_bf16 v[16:31], v[72:75], v[206:209], v[16:31]
	v_add_u32_e32 v64, s17, v183
	ds_write_b128 v64, v[128:131] offset:49152
	v_add_u32_e32 v64, s17, v188
	v_cmp_gt_f32_e32 vcc, 1.0, v200
	ds_write_b128 v64, v[136:139] offset:49152
	s_waitcnt lgkmcnt(6)
	v_mfma_f32_32x32x16_bf16 v[16:31], v[68:71], v[210:213], v[16:31]
	s_waitcnt lgkmcnt(4)
	v_mfma_f32_32x32x16_bf16 v[16:31], v[76:79], v[222:225], v[16:31]
	s_cbranch_vccz .LBB0_429
	s_and_saveexec_b64 s[4:5], s[0:1]
	ds_write_b32 v179, v200 offset:128
	s_or_b64 exec, exec, s[4:5]
	s_waitcnt lgkmcnt(0)
	v_add_u32_e32 v76, v177, v176
	ds_read_b128 v[64:67], v76 offset:224
	ds_read_b128 v[68:71], v76 offset:192
	ds_read_b128 v[72:75], v76 offset:160
	ds_read_b128 v[76:79], v76 offset:128
	s_waitcnt lgkmcnt(3)
	v_pk_mul_f32 v[12:13], v[12:13], v[64:65]
	s_waitcnt lgkmcnt(2)
	v_pk_mul_f32 v[8:9], v[8:9], v[68:69]
	s_waitcnt lgkmcnt(1)
	v_pk_mul_f32 v[4:5], v[4:5], v[72:73]
	v_pk_mul_f32 v[14:15], v[14:15], v[66:67]
	v_pk_mul_f32 v[10:11], v[10:11], v[70:71]
	v_pk_mul_f32 v[6:7], v[6:7], v[74:75]
	s_waitcnt lgkmcnt(0)
	v_pk_mul_f32 v[2:3], v[2:3], v[78:79]
	v_pk_mul_f32 v[0:1], v[0:1], v[76:77]
	v_pk_mul_f32 v[60:61], v[60:61], v[64:65]
	v_pk_mul_f32 v[56:57], v[56:57], v[68:69]
	v_pk_mul_f32 v[52:53], v[52:53], v[72:73]
	v_pk_mul_f32 v[62:63], v[62:63], v[66:67]
	v_pk_mul_f32 v[58:59], v[58:59], v[70:71]
	v_pk_mul_f32 v[54:55], v[54:55], v[74:75]
	v_pk_mul_f32 v[50:51], v[50:51], v[78:79]
	v_pk_mul_f32 v[48:49], v[48:49], v[76:77]
	v_pk_mul_f32 v[44:45], v[44:45], v[64:65]
	v_pk_mul_f32 v[40:41], v[40:41], v[68:69]
	v_pk_mul_f32 v[36:37], v[36:37], v[72:73]
	v_pk_mul_f32 v[46:47], v[46:47], v[66:67]
	v_pk_mul_f32 v[42:43], v[42:43], v[70:71]
	v_pk_mul_f32 v[38:39], v[38:39], v[74:75]
	v_pk_mul_f32 v[34:35], v[34:35], v[78:79]
	v_pk_mul_f32 v[32:33], v[32:33], v[76:77]
	v_pk_mul_f32 v[28:29], v[28:29], v[64:65]
	v_pk_mul_f32 v[24:25], v[24:25], v[68:69]
	v_pk_mul_f32 v[20:21], v[20:21], v[72:73]
	v_pk_mul_f32 v[30:31], v[30:31], v[66:67]
	v_pk_mul_f32 v[26:27], v[26:27], v[70:71]
	v_pk_mul_f32 v[22:23], v[22:23], v[74:75]
	v_pk_mul_f32 v[18:19], v[18:19], v[78:79]
	v_pk_mul_f32 v[16:17], v[16:17], v[76:77]
.LBB0_429:
	v_exp_f32_e32 v199, v96
	v_exp_f32_e32 v221, v97
	v_exp_f32_e32 v226, v98
	v_exp_f32_e32 v227, v99
	v_exp_f32_e32 v228, v100
	v_exp_f32_e32 v229, v101
	v_exp_f32_e32 v230, v102
	v_exp_f32_e32 v231, v103
	v_exp_f32_e32 v232, v104
	v_exp_f32_e32 v233, v105
	v_exp_f32_e32 v234, v106
	v_exp_f32_e32 v235, v107
	v_exp_f32_e32 v236, v108
	v_exp_f32_e32 v237, v109
	v_exp_f32_e32 v238, v110
	v_exp_f32_e32 v239, v111
	s_waitcnt lgkmcnt(0)
	s_barrier
	v_add_u32_e32 v96, s17, v185
	ds_read_b128 v[202:205], v96 offset:49152
	ds_read_b128 v[206:209], v96 offset:57344
	v_xor_b32_e32 v64, 0x80000000, v195
	v_mov_b32_e32 v65, v64
	v_mov_b64_e32 v[66:67], v[64:65]
	v_mov_b64_e32 v[68:69], v[64:65]
	v_mov_b64_e32 v[70:71], v[64:65]
	v_mov_b64_e32 v[72:73], v[64:65]
	v_mov_b64_e32 v[74:75], v[64:65]
	v_mov_b64_e32 v[76:77], v[64:65]
	v_mov_b64_e32 v[78:79], v[64:65]
	v_add_u32_e32 v201, s17, v189
	v_exp_f32_e32 v80, v80
	s_waitcnt lgkmcnt(1)
	v_mfma_f32_32x32x16_bf16 v[96:111], v[202:205], v[124:127], v[64:79]
	v_exp_f32_e32 v81, v81
	v_exp_f32_e32 v82, v82
	v_exp_f32_e32 v83, v83
	v_exp_f32_e32 v84, v84
	v_exp_f32_e32 v85, v85
	v_exp_f32_e32 v86, v86
	v_exp_f32_e32 v87, v87
	s_waitcnt lgkmcnt(0)
	v_mfma_f32_32x32x16_bf16 v[64:79], v[206:209], v[124:127], v[64:79]
	ds_read_b128 v[202:205], v201 offset:49152
	ds_read_b128 v[206:209], v201 offset:57344
	v_add_u32_e32 v201, s17, v192
	v_exp_f32_e32 v240, v91
	v_exp_f32_e32 v241, v92
	v_cvt_pk_bf16_f32 v91, v230, v231
	v_cvt_pk_bf16_f32 v92, v232, v233
	s_waitcnt lgkmcnt(1)
	v_mfma_f32_32x32x16_bf16 v[96:111], v[202:205], v[120:123], v[96:111]
	ds_read_b128 v[202:205], v201 offset:49152
	ds_read_b128 v[210:213], v201 offset:57344
	v_add_u32_e32 v201, s17, v194
	s_waitcnt lgkmcnt(1)
	v_mfma_f32_32x32x16_bf16 v[96:111], v[202:205], v[116:119], v[96:111]
	v_exp_f32_e32 v203, v88
	v_add_f32_e32 v88, 0, v199
	v_add_f32_e32 v88, v221, v88
	v_add_f32_e32 v88, v226, v88
	v_add_f32_e32 v88, v227, v88
	v_add_f32_e32 v88, v228, v88
	v_add_f32_e32 v88, v229, v88
	v_add_f32_e32 v88, v230, v88
	v_add_f32_e32 v88, v231, v88
	v_add_f32_e32 v88, v232, v88
	v_add_f32_e32 v88, v233, v88
	v_mfma_f32_32x32x16_bf16 v[64:79], v[206:209], v[120:123], v[64:79]
	v_add_f32_e32 v88, v234, v88
	v_add_f32_e32 v88, v235, v88
	v_add_f32_e32 v88, v236, v88
	v_add_f32_e32 v88, v237, v88
	v_add_f32_e32 v88, v238, v88
	v_add_f32_e32 v88, v239, v88
	v_add_f32_e32 v88, v80, v88
	v_add_f32_e32 v88, v81, v88
	s_waitcnt lgkmcnt(0)
	v_mfma_f32_32x32x16_bf16 v[64:79], v[210:213], v[116:119], v[64:79]
	v_add_f32_e32 v88, v82, v88
	v_add_f32_e32 v88, v83, v88
	v_add_f32_e32 v88, v84, v88
	ds_read_b128 v[206:209], v201 offset:49152
	ds_read_b128 v[222:225], v201 offset:57344
	v_exp_f32_e32 v204, v89
	v_add_f32_e32 v88, v85, v88
	v_exp_f32_e32 v205, v90
	v_add_f32_e32 v88, v86, v88
	v_add_f32_e32 v88, v87, v88
	v_add_f32_e32 v88, v203, v88
	v_exp_f32_e32 v210, v93
	v_add_f32_e32 v88, v204, v88
	v_exp_f32_e32 v211, v94
	s_waitcnt lgkmcnt(1)
	v_mfma_f32_32x32x16_bf16 v[96:111], v[206:209], v[112:115], v[96:111]
	v_add_f32_e32 v88, v205, v88
	v_exp_f32_e32 v212, v95
	v_add_f32_e32 v88, v240, v88
	v_add_f32_e32 v88, v241, v88
	v_add_f32_e32 v88, v210, v88
	v_add_f32_e32 v88, v211, v88
	v_add_f32_e32 v201, v212, v88
	s_waitcnt lgkmcnt(0)
	v_mfma_f32_32x32x16_bf16 v[64:79], v[222:225], v[112:115], v[64:79]
	v_mov_b32_e32 v202, v201
	v_cvt_pk_bf16_f32 v88, v199, v221
	v_cvt_pk_bf16_f32 v89, v226, v227
	v_cvt_pk_bf16_f32 v90, v228, v229
	v_cvt_pk_bf16_f32 v93, v234, v235
	v_cvt_pk_bf16_f32 v94, v236, v237
	v_cvt_pk_bf16_f32 v95, v238, v239
	v_cvt_pk_bf16_f32 v80, v80, v81
	v_cvt_pk_bf16_f32 v81, v82, v83
	v_cvt_pk_bf16_f32 v82, v84, v85
	v_cvt_pk_bf16_f32 v83, v86, v87
	v_cvt_pk_bf16_f32 v84, v203, v204
	v_cvt_pk_bf16_f32 v85, v205, v240
	v_cvt_pk_bf16_f32 v86, v241, v210
	v_cvt_pk_bf16_f32 v87, v211, v212
	v_permlane32_swap_b32_e32 v201, v202
	s_cmpk_gt_u32 s6, 0x7c
	s_cselect_b64 s[4:5], -1, 0
	s_and_b64 vcc, exec, s[4:5]
	s_cbranch_vccnz .Lattn_a0_lastw
	global_load_dwordx4 v[132:135], v244, s[98:99]
	global_load_dwordx4 v[128:131], v242, s[98:99]
	global_load_dwordx4 v[140:143], v245, s[98:99]
	global_load_dwordx4 v[136:139], v243, s[98:99]
	s_add_u32 s98, s98, 0x10000
	s_addc_u32 s99, s99, 0
.LBB0_431:
	v_add_u32_e32 v203, s16, v181
	ds_read_b64_tr_b16 v[204:205], v203 offset:0
	ds_read_b64_tr_b16 v[206:207], v203 offset:0x100
	ds_read_b64_tr_b16 v[208:209], v203 offset:0x1000
	ds_read_b64_tr_b16 v[210:211], v203 offset:0x1100
	ds_read_b64_tr_b16 v[222:223], v203 offset:0x2000
	ds_read_b64_tr_b16 v[224:225], v203 offset:0x2100
	ds_read_b64_tr_b16 v[226:227], v203 offset:0x3000
	ds_read_b64_tr_b16 v[228:229], v203 offset:0x3100
	s_waitcnt lgkmcnt(0)
	s_nop 0
	v_mfma_f32_32x32x16_bf16 v[0:15], v[88:91], v[204:207], v[0:15]
	v_max_f32_e32 v199, v97, v97
	v_max_f32_e32 v204, v96, v96
	v_max_f32_e32 v199, v204, v199
	ds_read_b64_tr_b16 v[204:205], v203 offset:0x200
	ds_read_b64_tr_b16 v[206:207], v203 offset:0x300
	v_max3_f32 v199, v199, v98, v99
	v_max3_f32 v199, v199, v100, v101
	v_mfma_f32_32x32x16_bf16 v[0:15], v[92:95], v[208:211], v[0:15]
	ds_read_b64_tr_b16 v[208:209], v203 offset:0x1200
	ds_read_b64_tr_b16 v[210:211], v203 offset:0x1300
	v_max3_f32 v199, v199, v102, v103
	v_max3_f32 v199, v199, v104, v105
	v_max3_f32 v199, v199, v106, v107
	v_max3_f32 v199, v199, v108, v109
	v_max3_f32 v199, v199, v110, v111
	v_mfma_f32_32x32x16_bf16 v[0:15], v[80:83], v[222:225], v[0:15]
	ds_read_b64_tr_b16 v[222:223], v203 offset:0x2200
	ds_read_b64_tr_b16 v[224:225], v203 offset:0x2300
	ds_read_b64_tr_b16 v[230:231], v203 offset:0x3200
	ds_read_b64_tr_b16 v[232:233], v203 offset:0x3300
	v_mfma_f32_32x32x16_bf16 v[0:15], v[84:87], v[226:229], v[0:15]
	s_waitcnt lgkmcnt(6)
	v_mfma_f32_32x32x16_bf16 v[48:63], v[88:91], v[204:207], v[48:63]
	v_max3_f32 v199, v199, v64, v65
	v_max3_f32 v199, v199, v66, v67
	ds_read_b64_tr_b16 v[206:207], v203 offset:0x400
	v_max3_f32 v199, v199, v68, v69
	v_max3_f32 v199, v199, v70, v71
	v_max3_f32 v199, v199, v72, v73
	v_max3_f32 v199, v199, v74, v75
	s_waitcnt lgkmcnt(5)
	v_mfma_f32_32x32x16_bf16 v[48:63], v[92:95], v[208:211], v[48:63]
	ds_read_b64_tr_b16 v[208:209], v203 offset:0x500
	ds_read_b64_tr_b16 v[210:211], v203 offset:0x1400
	ds_read_b64_tr_b16 v[212:213], v203 offset:0x1500
	v_max3_f32 v199, v199, v76, v77
	v_max3_f32 v199, v199, v78, v79
	v_mov_b32_e32 v204, v199
	s_nop 1
	v_permlane32_swap_b32_e32 v199, v204
	s_waitcnt lgkmcnt(6)
	v_mfma_f32_32x32x16_bf16 v[48:63], v[80:83], v[222:225], v[48:63]
	ds_read_b64_tr_b16 v[222:223], v203 offset:0x2400
	ds_read_b64_tr_b16 v[224:225], v203 offset:0x2500
	ds_read_b64_tr_b16 v[226:227], v203 offset:0x3400
	ds_read_b64_tr_b16 v[228:229], v203 offset:0x3500
	v_max_f32_e32 v204, v204, v204
	v_max_f32_e32 v199, v199, v199
	s_waitcnt lgkmcnt(8)
	v_mfma_f32_32x32x16_bf16 v[48:63], v[84:87], v[230:233], v[48:63]
	v_max_f32_e32 v204, v199, v204
	s_waitcnt lgkmcnt(6)
	v_mfma_f32_32x32x16_bf16 v[32:47], v[88:91], v[206:209], v[32:47]
	v_cmp_ge_f32_e32 vcc, s63, v204
	s_cmp_eq_u64 vcc, exec
	v_mov_b32_e32 v199, 1.0
	s_waitcnt lgkmcnt(4)
	v_mfma_f32_32x32x16_bf16 v[32:47], v[92:95], v[210:213], v[32:47]
	s_waitcnt lgkmcnt(2)
	v_mfma_f32_32x32x16_bf16 v[32:47], v[80:83], v[222:225], v[32:47]
	s_waitcnt lgkmcnt(0)
	v_mfma_f32_32x32x16_bf16 v[32:47], v[84:87], v[226:229], v[32:47]
	s_cbranch_scc0 .LBB0_439
.LBB0_432:
	ds_read_b64_tr_b16 v[204:205], v203 offset:0x600
	ds_read_b64_tr_b16 v[206:207], v203 offset:0x700
	ds_read_b64_tr_b16 v[208:209], v203 offset:0x1600
	ds_read_b64_tr_b16 v[210:211], v203 offset:0x1700
	ds_read_b64_tr_b16 v[222:223], v203 offset:0x2600
	ds_read_b64_tr_b16 v[224:225], v203 offset:0x2700
	ds_read_b64_tr_b16 v[226:227], v203 offset:0x3600
	ds_read_b64_tr_b16 v[228:229], v203 offset:0x3700
	s_add_i32 s16, s18, 1
	s_cmp_lg_u32 s18, 2
	s_cselect_b32 s19, s16, 0
	s_waitcnt lgkmcnt(6)
	v_mfma_f32_32x32x16_bf16 v[16:31], v[88:91], v[204:207], v[16:31]
	s_lshl_b32 s16, s19, 14
	s_add_i32 s16, s16, 16
	s_waitcnt vmcnt(4)
	v_add_u32_e32 v88, s16, v184
	ds_write_b128 v88, v[144:147]
	v_cmp_gt_f32_e32 vcc, 1.0, v199
	s_waitcnt lgkmcnt(5)
	v_mfma_f32_32x32x16_bf16 v[16:31], v[92:95], v[208:211], v[16:31]
	s_waitcnt lgkmcnt(3)
	v_mfma_f32_32x32x16_bf16 v[16:31], v[80:83], v[222:225], v[16:31]
	v_add_u32_e32 v80, s16, v186
	ds_write_b128 v80, v[148:151]
	v_add_u32_e32 v80, s16, v183
	ds_write_b128 v80, v[152:155] offset:49152
	v_add_u32_e32 v80, s16, v188
	ds_write_b128 v80, v[156:159] offset:49152
	s_waitcnt lgkmcnt(4)
	v_mfma_f32_32x32x16_bf16 v[16:31], v[84:87], v[226:229], v[16:31]
	s_cbranch_vccz .LBB0_436
	s_and_saveexec_b64 s[16:17], s[0:1]
	ds_write_b32 v179, v199 offset:128
	s_or_b64 exec, exec, s[16:17]
	s_waitcnt lgkmcnt(0)
	v_add_u32_e32 v92, v177, v176
	ds_read_b128 v[80:83], v92 offset:224
	ds_read_b128 v[84:87], v92 offset:192
	ds_read_b128 v[88:91], v92 offset:160
	ds_read_b128 v[92:95], v92 offset:128
	s_waitcnt lgkmcnt(3)
	v_pk_mul_f32 v[12:13], v[12:13], v[80:81]
	s_waitcnt lgkmcnt(2)
	v_pk_mul_f32 v[8:9], v[8:9], v[84:85]
	s_waitcnt lgkmcnt(1)
	v_pk_mul_f32 v[4:5], v[4:5], v[88:89]
	v_pk_mul_f32 v[14:15], v[14:15], v[82:83]
	v_pk_mul_f32 v[10:11], v[10:11], v[86:87]
	v_pk_mul_f32 v[6:7], v[6:7], v[90:91]
	s_waitcnt lgkmcnt(0)
	v_pk_mul_f32 v[2:3], v[2:3], v[94:95]
	v_pk_mul_f32 v[0:1], v[0:1], v[92:93]
	v_pk_mul_f32 v[60:61], v[60:61], v[80:81]
	v_pk_mul_f32 v[56:57], v[56:57], v[84:85]
	v_pk_mul_f32 v[52:53], v[52:53], v[88:89]
	v_pk_mul_f32 v[62:63], v[62:63], v[82:83]
	v_pk_mul_f32 v[58:59], v[58:59], v[86:87]
	v_pk_mul_f32 v[54:55], v[54:55], v[90:91]
	v_pk_mul_f32 v[50:51], v[50:51], v[94:95]
	v_pk_mul_f32 v[48:49], v[48:49], v[92:93]
	v_pk_mul_f32 v[44:45], v[44:45], v[80:81]
	v_pk_mul_f32 v[40:41], v[40:41], v[84:85]
	v_pk_mul_f32 v[36:37], v[36:37], v[88:89]
	v_pk_mul_f32 v[46:47], v[46:47], v[82:83]
	v_pk_mul_f32 v[42:43], v[42:43], v[86:87]
	v_pk_mul_f32 v[38:39], v[38:39], v[90:91]
	v_pk_mul_f32 v[34:35], v[34:35], v[94:95]
	v_pk_mul_f32 v[32:33], v[32:33], v[92:93]
	v_pk_mul_f32 v[28:29], v[28:29], v[80:81]
	v_pk_mul_f32 v[24:25], v[24:25], v[84:85]
	v_pk_mul_f32 v[20:21], v[20:21], v[88:89]
	v_pk_mul_f32 v[30:31], v[30:31], v[82:83]
	v_pk_mul_f32 v[26:27], v[26:27], v[86:87]
	v_pk_mul_f32 v[22:23], v[22:23], v[90:91]
	v_pk_mul_f32 v[18:19], v[18:19], v[94:95]
	v_pk_mul_f32 v[16:17], v[16:17], v[92:93]

.LBB0_440:
	v_or_b32_e32 v136, 0x2000, v190
	v_add_u32_e32 v90, s58, v185
	v_add3_u32 v96, v182, v136, s58
	ds_read_b128 v[128:131], v90
	ds_read_b128 v[132:135], v96
	v_xor_b32_e32 v80, 0x80000000, v195
	v_mov_b32_e32 v81, v80
	v_mov_b64_e32 v[82:83], v[80:81]
	v_mov_b64_e32 v[84:85], v[80:81]
	v_mov_b64_e32 v[86:87], v[80:81]
	v_mov_b64_e32 v[88:89], v[80:81]
	v_mov_b64_e32 v[90:91], v[80:81]
	v_mov_b64_e32 v[92:93], v[80:81]
	v_mov_b64_e32 v[94:95], v[80:81]
	v_exp_f32_e32 v137, v65
	v_exp_f32_e32 v138, v70
	s_waitcnt lgkmcnt(1)
	v_mfma_f32_32x32x16_bf16 v[96:111], v[128:131], v[124:127], v[80:95]
	v_add3_u32 v128, v187, v136, s58
	ds_read_b128 v[128:131], v128
	v_exp_f32_e32 v139, v71
	v_exp_f32_e32 v140, v72
	v_exp_f32_e32 v79, v79
	v_cvt_pk_bf16_f32 v65, v154, v155
	v_cvt_pk_bf16_f32 v70, v148, v149
	s_waitcnt lgkmcnt(1)
	v_mfma_f32_32x32x16_bf16 v[80:95], v[132:135], v[124:127], v[80:95]
	v_add_u32_e32 v124, s58, v189
	ds_read_b128 v[124:127], v124
	v_add3_u32 v132, v191, v136, s58
	v_cvt_pk_bf16_f32 v71, v150, v151
	s_waitcnt lgkmcnt(0)
	v_mfma_f32_32x32x16_bf16 v[96:111], v[124:127], v[120:123], v[96:111]
	v_add_u32_e32 v124, s58, v192
	ds_read_b128 v[124:127], v124
	v_mfma_f32_32x32x16_bf16 v[80:95], v[128:131], v[120:123], v[80:95]
	ds_read_b128 v[120:123], v132
	v_add3_u32 v132, v193, v136, s58
	v_exp_f32_e32 v136, v64
	v_add_f32_e32 v64, 0, v152
	v_add_f32_e32 v64, v153, v64
	v_add_f32_e32 v64, v154, v64
	v_add_f32_e32 v64, v155, v64
	v_add_f32_e32 v64, v156, v64
	v_add_f32_e32 v64, v157, v64
	v_add_f32_e32 v64, v158, v64
	v_add_f32_e32 v64, v159, v64
	v_add_f32_e32 v64, v144, v64
	v_add_f32_e32 v64, v145, v64
	v_add_f32_e32 v64, v146, v64
	v_add_f32_e32 v64, v147, v64
	v_add_f32_e32 v64, v148, v64
	v_add_f32_e32 v64, v149, v64
	s_waitcnt lgkmcnt(1)
	v_mfma_f32_32x32x16_bf16 v[96:111], v[124:127], v[116:119], v[96:111]
	v_exp_f32_e32 v124, v66
	v_add_f32_e32 v64, v150, v64
	v_exp_f32_e32 v125, v67
	v_add_f32_e32 v64, v151, v64
	v_exp_f32_e32 v126, v68
	v_add_f32_e32 v64, v136, v64
	v_exp_f32_e32 v127, v69
	v_add_f32_e32 v64, v137, v64
	s_waitcnt lgkmcnt(0)
	v_mfma_f32_32x32x16_bf16 v[80:95], v[120:123], v[116:119], v[80:95]
	v_add_f32_e32 v64, v124, v64
	v_add_f32_e32 v64, v125, v64
	v_add_u32_e32 v128, s58, v194
	v_add_f32_e32 v64, v126, v64
	ds_read_b128 v[128:131], v128
	ds_read_b128 v[132:135], v132
	v_exp_f32_e32 v116, v73
	v_add_f32_e32 v64, v127, v64
	v_exp_f32_e32 v117, v74
	v_add_f32_e32 v64, v138, v64
	v_exp_f32_e32 v118, v75
	v_add_f32_e32 v64, v139, v64
	v_exp_f32_e32 v119, v76
	v_add_f32_e32 v64, v140, v64
	v_exp_f32_e32 v120, v77
	v_add_f32_e32 v64, v116, v64
	v_exp_f32_e32 v121, v78
	s_waitcnt lgkmcnt(1)
	v_mfma_f32_32x32x16_bf16 v[96:111], v[128:131], v[112:115], v[96:111]
	v_add_f32_e32 v64, v117, v64
	v_add_f32_e32 v64, v118, v64
	v_add_f32_e32 v64, v119, v64
	v_add_f32_e32 v64, v120, v64
	v_add_f32_e32 v64, v121, v64
	v_cvt_pk_bf16_f32 v66, v156, v157
	v_cvt_pk_bf16_f32 v67, v158, v159
	s_waitcnt lgkmcnt(0)
	v_mfma_f32_32x32x16_bf16 v[80:95], v[132:135], v[112:115], v[80:95]
	v_add_f32_e32 v112, v79, v64
	v_mov_b32_e32 v113, v112
	v_cvt_pk_bf16_f32 v64, v152, v153
	v_cvt_pk_bf16_f32 v68, v144, v145
	v_cvt_pk_bf16_f32 v69, v146, v147
	v_cvt_pk_bf16_f32 v72, v136, v137
	v_cvt_pk_bf16_f32 v73, v124, v125
	v_cvt_pk_bf16_f32 v74, v126, v127
	v_cvt_pk_bf16_f32 v75, v138, v139
	v_cvt_pk_bf16_f32 v76, v140, v116
	v_cvt_pk_bf16_f32 v77, v117, v118
	v_cvt_pk_bf16_f32 v78, v119, v120
	v_cvt_pk_bf16_f32 v79, v121, v79
	v_permlane32_swap_b32_e32 v112, v113
	ds_read_b64_tr_b16 v[114:115], v181 offset:0
	ds_read_b64_tr_b16 v[116:117], v181 offset:0x100
	ds_read_b64_tr_b16 v[118:119], v181 offset:0x1000
	ds_read_b64_tr_b16 v[120:121], v181 offset:0x1100
	ds_read_b64_tr_b16 v[122:123], v181 offset:0x2000
	ds_read_b64_tr_b16 v[124:125], v181 offset:0x2100
	ds_read_b64_tr_b16 v[126:127], v181 offset:0x3000
	ds_read_b64_tr_b16 v[128:129], v181 offset:0x3100
	s_waitcnt lgkmcnt(0)
	s_nop 0
	v_mfma_f32_32x32x16_bf16 v[0:15], v[64:67], v[114:117], v[0:15]
	v_max_f32_e32 v114, v97, v97
	v_max_f32_e32 v115, v96, v96
	v_max_f32_e32 v114, v115, v114
	v_max3_f32 v114, v114, v98, v99
	v_max3_f32 v114, v114, v100, v101
	v_max3_f32 v114, v114, v102, v103
	v_max3_f32 v114, v114, v104, v105
	v_mfma_f32_32x32x16_bf16 v[0:15], v[68:71], v[118:121], v[0:15]
	v_max3_f32 v114, v114, v106, v107
	v_max3_f32 v116, v114, v108, v109
	ds_read_b64_tr_b16 v[114:115], v181 offset:0x200
	v_max3_f32 v134, v116, v110, v111
	ds_read_b64_tr_b16 v[116:117], v181 offset:0x300
	ds_read_b64_tr_b16 v[118:119], v181 offset:0x1200
	ds_read_b64_tr_b16 v[120:121], v181 offset:0x1300
	v_mfma_f32_32x32x16_bf16 v[0:15], v[72:75], v[122:125], v[0:15]
	ds_read_b64_tr_b16 v[122:123], v181 offset:0x2200
	ds_read_b64_tr_b16 v[124:125], v181 offset:0x2300
	ds_read_b64_tr_b16 v[130:131], v181 offset:0x3200
	ds_read_b64_tr_b16 v[132:133], v181 offset:0x3300
	s_waitcnt lgkmcnt(0)
	v_mfma_f32_32x32x16_bf16 v[0:15], v[76:79], v[126:129], v[0:15]
	v_mfma_f32_32x32x16_bf16 v[48:63], v[64:67], v[114:117], v[48:63]
	v_max3_f32 v126, v134, v80, v81
	v_max3_f32 v114, v126, v82, v83
	ds_read_b64_tr_b16 v[116:117], v181 offset:0x400
	v_max3_f32 v114, v114, v84, v85
	v_max3_f32 v114, v114, v86, v87
	v_max3_f32 v114, v114, v88, v89
	v_max3_f32 v114, v114, v90, v91
	v_mfma_f32_32x32x16_bf16 v[48:63], v[68:71], v[118:121], v[48:63]
	ds_read_b64_tr_b16 v[118:119], v181 offset:0x500
	ds_read_b64_tr_b16 v[120:121], v181 offset:0x1400
	v_max3_f32 v114, v114, v92, v93
	v_max3_f32 v114, v114, v94, v95
	v_mov_b32_e32 v115, v114
	s_nop 1
	v_permlane32_swap_b32_e32 v114, v115
	v_mfma_f32_32x32x16_bf16 v[48:63], v[72:75], v[122:125], v[48:63]
	ds_read_b64_tr_b16 v[122:123], v181 offset:0x1500
	ds_read_b64_tr_b16 v[124:125], v181 offset:0x2400
	ds_read_b64_tr_b16 v[126:127], v181 offset:0x2500
	ds_read_b64_tr_b16 v[134:135], v181 offset:0x3400
	ds_read_b64_tr_b16 v[136:137], v181 offset:0x3500
	s_waitcnt lgkmcnt(0)
	v_max_f32_e32 v115, v115, v115
	v_mfma_f32_32x32x16_bf16 v[48:63], v[76:79], v[130:133], v[48:63]
	v_max_f32_e32 v114, v114, v114
	v_max_f32_e32 v115, v114, v115
	v_mfma_f32_32x32x16_bf16 v[32:47], v[64:67], v[116:119], v[32:47]
	v_cmp_ge_f32_e32 vcc, s63, v115
	s_cmp_eq_u64 vcc, exec
	v_mov_b32_e32 v114, 1.0
	v_mfma_f32_32x32x16_bf16 v[32:47], v[68:71], v[120:123], v[32:47]
	v_mfma_f32_32x32x16_bf16 v[32:47], v[72:75], v[124:127], v[32:47]
	v_mfma_f32_32x32x16_bf16 v[32:47], v[76:79], v[134:137], v[32:47]
	s_cbranch_scc0 .LBB0_451
.LBB0_441:
	ds_read_b64_tr_b16 v[116:117], v181 offset:0x600
	ds_read_b64_tr_b16 v[118:119], v181 offset:0x700
	ds_read_b64_tr_b16 v[120:121], v181 offset:0x1600
	ds_read_b64_tr_b16 v[122:123], v181 offset:0x1700
	ds_read_b64_tr_b16 v[124:125], v181 offset:0x2600
	ds_read_b64_tr_b16 v[126:127], v181 offset:0x2700
	ds_read_b64_tr_b16 v[128:129], v181 offset:0x3600
	ds_read_b64_tr_b16 v[130:131], v181 offset:0x3700
	s_waitcnt lgkmcnt(0)
	s_nop 0
	v_mfma_f32_32x32x16_bf16 v[16:31], v[64:67], v[116:119], v[16:31]
	v_cmp_gt_f32_e32 vcc, 1.0, v114
	v_mfma_f32_32x32x16_bf16 v[16:31], v[68:71], v[120:123], v[16:31]
	v_mfma_f32_32x32x16_bf16 v[16:31], v[72:75], v[124:127], v[16:31]
	v_mfma_f32_32x32x16_bf16 v[16:31], v[76:79], v[128:131], v[16:31]
	s_cbranch_vccz .LBB0_445
	s_and_saveexec_b64 s[4:5], s[0:1]
	ds_write_b32 v179, v114 offset:128
	s_or_b64 exec, exec, s[4:5]
	s_waitcnt lgkmcnt(0)
	v_add_u32_e32 v76, v177, v176
	ds_read_b128 v[64:67], v76 offset:224
	ds_read_b128 v[68:71], v76 offset:192
	ds_read_b128 v[72:75], v76 offset:160
	ds_read_b128 v[76:79], v76 offset:128
	s_waitcnt lgkmcnt(3)
	v_pk_mul_f32 v[12:13], v[12:13], v[64:65]
	s_waitcnt lgkmcnt(2)
	v_pk_mul_f32 v[8:9], v[8:9], v[68:69]
	s_waitcnt lgkmcnt(1)
	v_pk_mul_f32 v[4:5], v[4:5], v[72:73]
	v_pk_mul_f32 v[14:15], v[14:15], v[66:67]
	v_pk_mul_f32 v[10:11], v[10:11], v[70:71]
	v_pk_mul_f32 v[6:7], v[6:7], v[74:75]
	s_waitcnt lgkmcnt(0)
	v_pk_mul_f32 v[2:3], v[2:3], v[78:79]
	v_pk_mul_f32 v[0:1], v[0:1], v[76:77]
	v_pk_mul_f32 v[60:61], v[60:61], v[64:65]
	v_pk_mul_f32 v[56:57], v[56:57], v[68:69]
	v_pk_mul_f32 v[52:53], v[52:53], v[72:73]
	v_pk_mul_f32 v[62:63], v[62:63], v[66:67]
	v_pk_mul_f32 v[58:59], v[58:59], v[70:71]
	v_pk_mul_f32 v[54:55], v[54:55], v[74:75]
	v_pk_mul_f32 v[50:51], v[50:51], v[78:79]
	v_pk_mul_f32 v[48:49], v[48:49], v[76:77]
	v_pk_mul_f32 v[44:45], v[44:45], v[64:65]
	v_pk_mul_f32 v[40:41], v[40:41], v[68:69]
	v_pk_mul_f32 v[36:37], v[36:37], v[72:73]
	v_pk_mul_f32 v[46:47], v[46:47], v[66:67]
	v_pk_mul_f32 v[42:43], v[42:43], v[70:71]
	v_pk_mul_f32 v[38:39], v[38:39], v[74:75]
	v_pk_mul_f32 v[34:35], v[34:35], v[78:79]
	v_pk_mul_f32 v[32:33], v[32:33], v[76:77]
	v_pk_mul_f32 v[28:29], v[28:29], v[64:65]
	v_pk_mul_f32 v[24:25], v[24:25], v[68:69]
	v_pk_mul_f32 v[20:21], v[20:21], v[72:73]
	v_pk_mul_f32 v[30:31], v[30:31], v[66:67]
	v_pk_mul_f32 v[26:27], v[26:27], v[70:71]
	v_pk_mul_f32 v[22:23], v[22:23], v[74:75]
	v_pk_mul_f32 v[18:19], v[18:19], v[78:79]
	v_pk_mul_f32 v[16:17], v[16:17], v[76:77]
.LBB0_445:
	v_exp_f32_e32 v66, v96
	v_exp_f32_e32 v67, v97
	v_exp_f32_e32 v68, v98
	v_exp_f32_e32 v69, v99
	v_exp_f32_e32 v70, v100
	v_add_f32_e32 v64, 0, v66
	v_exp_f32_e32 v71, v101
	v_add_f32_e32 v64, v67, v64
	v_exp_f32_e32 v72, v102
	v_add_f32_e32 v64, v68, v64
	v_exp_f32_e32 v73, v103
	v_add_f32_e32 v64, v69, v64
	v_exp_f32_e32 v74, v104
	v_add_f32_e32 v64, v70, v64
	v_exp_f32_e32 v75, v105
	v_add_f32_e32 v64, v71, v64
	v_exp_f32_e32 v76, v106
	v_add_f32_e32 v64, v72, v64
	v_exp_f32_e32 v77, v107
	v_add_f32_e32 v64, v73, v64
	v_exp_f32_e32 v78, v108
	v_add_f32_e32 v64, v74, v64
	v_exp_f32_e32 v79, v109
	v_add_f32_e32 v64, v75, v64
	v_exp_f32_e32 v96, v110
	v_add_f32_e32 v64, v76, v64
	v_exp_f32_e32 v97, v111
	v_add_f32_e32 v64, v77, v64
	v_exp_f32_e32 v80, v80
	v_add_f32_e32 v64, v78, v64
	v_exp_f32_e32 v81, v81
	v_add_f32_e32 v64, v79, v64
	v_exp_f32_e32 v82, v82
	v_add_f32_e32 v64, v96, v64
	v_exp_f32_e32 v83, v83
	v_add_f32_e32 v64, v97, v64
	v_exp_f32_e32 v84, v84
	v_add_f32_e32 v64, v80, v64
	v_exp_f32_e32 v85, v85
	v_add_f32_e32 v64, v81, v64
	v_exp_f32_e32 v86, v86
	v_add_f32_e32 v64, v82, v64
	v_exp_f32_e32 v87, v87
	v_add_f32_e32 v64, v83, v64
	v_exp_f32_e32 v88, v88
	v_add_f32_e32 v64, v84, v64
	v_exp_f32_e32 v89, v89
	v_add_f32_e32 v64, v85, v64
	v_exp_f32_e32 v90, v90
	v_add_f32_e32 v64, v86, v64
	v_exp_f32_e32 v91, v91
	v_add_f32_e32 v64, v87, v64
	v_exp_f32_e32 v92, v92
	v_add_f32_e32 v64, v88, v64
	v_exp_f32_e32 v93, v93
	v_add_f32_e32 v64, v89, v64
	v_exp_f32_e32 v94, v94
	v_add_f32_e32 v64, v90, v64
	v_exp_f32_e32 v95, v95
	v_add_f32_e32 v64, v91, v64
	v_add_f32_e32 v64, v92, v64
	v_add_f32_e32 v64, v93, v64
	v_add_f32_e32 v64, v94, v64
	v_add_f32_e32 v64, v95, v64
	v_mov_b32_e32 v65, v64
	s_nop 1
	v_permlane32_swap_b32_e32 v64, v65
	v_cvt_pk_bf16_f32 v66, v66, v67
	v_cvt_pk_bf16_f32 v67, v68, v69
	v_cvt_pk_bf16_f32 v68, v70, v71
	v_cvt_pk_bf16_f32 v69, v72, v73
	v_cvt_pk_bf16_f32 v70, v74, v75
	v_cvt_pk_bf16_f32 v71, v76, v77
	v_cvt_pk_bf16_f32 v72, v78, v79
	v_cvt_pk_bf16_f32 v73, v96, v97
	v_cvt_pk_bf16_f32 v74, v80, v81
	v_cvt_pk_bf16_f32 v75, v82, v83
	v_cvt_pk_bf16_f32 v76, v84, v85
	v_cvt_pk_bf16_f32 v77, v86, v87
	v_cvt_pk_bf16_f32 v78, v88, v89
	v_cvt_pk_bf16_f32 v79, v90, v91
	v_cvt_pk_bf16_f32 v80, v92, v93
	v_cvt_pk_bf16_f32 v81, v94, v95
	s_cmp_lg_u32 16, -1
	s_cselect_b32 s4, 16, 0
	s_addk_i32 s4, 0x4000
	v_add_u32_e32 v102, s4, v178
	ds_read_b64_tr_b16 v[82:83], v102 offset:0
	ds_read_b64_tr_b16 v[84:85], v102 offset:0x100
	ds_read_b64_tr_b16 v[86:87], v102 offset:0x1000
	ds_read_b64_tr_b16 v[88:89], v102 offset:0x1100
	ds_read_b64_tr_b16 v[90:91], v102 offset:0x2000
	ds_read_b64_tr_b16 v[92:93], v102 offset:0x2100
	ds_read_b64_tr_b16 v[94:95], v102 offset:0x3000
	ds_read_b64_tr_b16 v[96:97], v102 offset:0x3100
	s_waitcnt lgkmcnt(0)
	s_nop 0
	v_mfma_f32_32x32x16_bf16 v[0:15], v[66:69], v[82:85], v[0:15]
	ds_read_b64_tr_b16 v[82:83], v102 offset:0x200
	ds_read_b64_tr_b16 v[84:85], v102 offset:0x300
	v_mfma_f32_32x32x16_bf16 v[0:15], v[70:73], v[86:89], v[0:15]
	ds_read_b64_tr_b16 v[86:87], v102 offset:0x1200
	ds_read_b64_tr_b16 v[88:89], v102 offset:0x1300
	v_mfma_f32_32x32x16_bf16 v[0:15], v[74:77], v[90:93], v[0:15]
	ds_read_b64_tr_b16 v[90:91], v102 offset:0x2200
	ds_read_b64_tr_b16 v[92:93], v102 offset:0x2300
	ds_read_b64_tr_b16 v[98:99], v102 offset:0x3200
	ds_read_b64_tr_b16 v[100:101], v102 offset:0x3300
	s_waitcnt lgkmcnt(0)
	v_mfma_f32_32x32x16_bf16 v[0:15], v[78:81], v[94:97], v[0:15]
	v_mfma_f32_32x32x16_bf16 v[48:63], v[66:69], v[82:85], v[48:63]
	ds_read_b64_tr_b16 v[82:83], v102 offset:0x400
	ds_read_b64_tr_b16 v[84:85], v102 offset:0x500
	v_mfma_f32_32x32x16_bf16 v[48:63], v[70:73], v[86:89], v[48:63]
	ds_read_b64_tr_b16 v[86:87], v102 offset:0x1400
	ds_read_b64_tr_b16 v[88:89], v102 offset:0x1500
	v_mfma_f32_32x32x16_bf16 v[48:63], v[74:77], v[90:93], v[48:63]
	ds_read_b64_tr_b16 v[90:91], v102 offset:0x2400
	ds_read_b64_tr_b16 v[92:93], v102 offset:0x2500
	ds_read_b64_tr_b16 v[94:95], v102 offset:0x3400
	ds_read_b64_tr_b16 v[96:97], v102 offset:0x3500
	s_waitcnt lgkmcnt(0)
	v_mfma_f32_32x32x16_bf16 v[48:63], v[78:81], v[98:101], v[48:63]
	v_mfma_f32_32x32x16_bf16 v[32:47], v[66:69], v[82:85], v[32:47]
	ds_read_b64_tr_b16 v[82:83], v102 offset:0x600
	ds_read_b64_tr_b16 v[84:85], v102 offset:0x700
	v_mfma_f32_32x32x16_bf16 v[32:47], v[70:73], v[86:89], v[32:47]
	ds_read_b64_tr_b16 v[86:87], v102 offset:0x1600
	ds_read_b64_tr_b16 v[88:89], v102 offset:0x1700
	v_mfma_f32_32x32x16_bf16 v[32:47], v[74:77], v[90:93], v[32:47]
	ds_read_b64_tr_b16 v[90:91], v102 offset:0x2600
	ds_read_b64_tr_b16 v[92:93], v102 offset:0x2700
	ds_read_b64_tr_b16 v[98:99], v102 offset:0x3600
	ds_read_b64_tr_b16 v[100:101], v102 offset:0x3700
	s_waitcnt lgkmcnt(0)
	v_mfma_f32_32x32x16_bf16 v[32:47], v[78:81], v[94:97], v[32:47]
	v_mfma_f32_32x32x16_bf16 v[16:31], v[66:69], v[82:85], v[16:31]
	v_mfma_f32_32x32x16_bf16 v[16:31], v[70:73], v[86:89], v[16:31]
	v_mfma_f32_32x32x16_bf16 v[16:31], v[74:77], v[90:93], v[16:31]
	v_mfma_f32_32x32x16_bf16 v[16:31], v[78:81], v[98:101], v[16:31]
	s_and_saveexec_b64 s[4:5], s[0:1]
	v_add_f32_e32 v66, v112, v113
	v_fmac_f32_e32 v66, v180, v199
	v_add_f32_e32 v64, v64, v65
	v_fmac_f32_e32 v64, v66, v114
	ds_write_b32 v179, v64
	s_or_b64 exec, exec, s[4:5]
	s_waitcnt lgkmcnt(0)
	v_add_u32_e32 v64, v177, v176
	ds_read_b128 v[68:71], v64
	ds_read_b128 v[72:75], v64 offset:32
	v_lshrrev_b32_e32 v67, 6, v174
	v_cmp_eq_u32_e32 vcc, 1, v175
	ds_read_b128 v[98:101], v64 offset:96
	s_waitcnt lgkmcnt(2)
	v_rcp_f32_e32 v96, v68
	v_rcp_f32_e32 v94, v69
	v_rcp_f32_e32 v92, v70
	v_rcp_f32_e32 v90, v71
	ds_read_b128 v[68:71], v64 offset:64
	s_waitcnt lgkmcnt(2)
	v_rcp_f32_e32 v88, v72
	v_rcp_f32_e32 v86, v73
	v_rcp_f32_e32 v84, v74
	v_rcp_f32_e32 v82, v75
	s_waitcnt lgkmcnt(0)
	v_rcp_f32_e32 v80, v68
	v_rcp_f32_e32 v78, v69
	v_rcp_f32_e32 v76, v70
	v_rcp_f32_e32 v74, v71
	v_rcp_f32_e32 v72, v98
	v_rcp_f32_e32 v70, v99
	v_rcp_f32_e32 v66, v100
	v_rcp_f32_e32 v64, v101
	v_lshlrev_b32_e32 v71, 11, v172
	s_barrier
	s_and_saveexec_b64 s[0:1], vcc
	s_cbranch_execz .LBB0_449
	v_lshlrev_b32_e32 v65, 14, v67
	v_and_b32_e32 v65, 0xc000, v65
	v_lshl_add_u32 v68, v173, 2, 16
	v_add3_u32 v65, v68, v71, v65
	v_mul_f32_e32 v68, v0, v96
	v_mul_f32_e32 v69, v48, v96
	ds_write2_b32 v65, v68, v69 offset1:32
	v_mul_f32_e32 v68, v32, v96
	v_mul_f32_e32 v69, v16, v96
	ds_write2_b32 v65, v68, v69 offset0:64 offset1:96
	v_mul_f32_e32 v68, v1, v94
	v_mul_f32_e32 v69, v49, v94
	ds_write2_b32 v65, v68, v69 offset0:128 offset1:160
	v_mul_f32_e32 v68, v33, v94
	v_mul_f32_e32 v69, v17, v94
	ds_write2_b32 v65, v68, v69 offset0:192 offset1:224
	v_mul_f32_e32 v68, v2, v92
	v_mul_f32_e32 v69, v50, v92
	v_add_u32_e32 v73, 0x400, v65
	ds_write2_b32 v73, v68, v69 offset1:32
	v_mul_f32_e32 v68, v34, v92
	v_mul_f32_e32 v69, v18, v92
	ds_write2_b32 v73, v68, v69 offset0:64 offset1:96
	v_mul_f32_e32 v68, v3, v90
	v_mul_f32_e32 v69, v51, v90
	ds_write2_b32 v73, v68, v69 offset0:128 offset1:160
	v_mul_f32_e32 v68, v35, v90
	v_mul_f32_e32 v69, v19, v90
	ds_write2_b32 v73, v68, v69 offset0:192 offset1:224
	v_mul_f32_e32 v68, v4, v88
	v_mul_f32_e32 v69, v52, v88
	v_add_u32_e32 v73, 0x1000, v65
	ds_write2_b32 v73, v68, v69 offset1:32
	v_mul_f32_e32 v68, v36, v88
	v_mul_f32_e32 v69, v20, v88
	ds_write2_b32 v73, v68, v69 offset0:64 offset1:96
	v_mul_f32_e32 v68, v5, v86
	v_mul_f32_e32 v69, v53, v86
	ds_write2_b32 v73, v68, v69 offset0:128 offset1:160
	v_mul_f32_e32 v68, v37, v86
	v_mul_f32_e32 v69, v21, v86
	ds_write2_b32 v73, v68, v69 offset0:192 offset1:224
	v_mul_f32_e32 v68, v6, v84
	v_mul_f32_e32 v69, v54, v84
	v_add_u32_e32 v73, 0x1400, v65
	ds_write2_b32 v73, v68, v69 offset1:32
	v_mul_f32_e32 v68, v38, v84
	v_mul_f32_e32 v69, v22, v84
	ds_write2_b32 v73, v68, v69 offset0:64 offset1:96
	v_mul_f32_e32 v68, v7, v82
	v_mul_f32_e32 v69, v55, v82
	ds_write2_b32 v73, v68, v69 offset0:128 offset1:160
	v_mul_f32_e32 v68, v39, v82
	v_mul_f32_e32 v69, v23, v82
	ds_write2_b32 v73, v68, v69 offset0:192 offset1:224
	v_mul_f32_e32 v68, v8, v80
	v_mul_f32_e32 v69, v56, v80
	v_add_u32_e32 v73, 0x2000, v65
	ds_write2_b32 v73, v68, v69 offset1:32
	v_mul_f32_e32 v68, v40, v80
	v_mul_f32_e32 v69, v24, v80
	ds_write2_b32 v73, v68, v69 offset0:64 offset1:96
	v_mul_f32_e32 v68, v9, v78
	v_mul_f32_e32 v69, v57, v78
	ds_write2_b32 v73, v68, v69 offset0:128 offset1:160
	v_mul_f32_e32 v68, v41, v78
	v_mul_f32_e32 v69, v25, v78
	ds_write2_b32 v73, v68, v69 offset0:192 offset1:224
	v_mul_f32_e32 v68, v10, v76
	v_mul_f32_e32 v69, v58, v76
	v_add_u32_e32 v73, 0x2400, v65
	ds_write2_b32 v73, v68, v69 offset1:32
	v_mul_f32_e32 v68, v42, v76
	v_mul_f32_e32 v69, v26, v76
	ds_write2_b32 v73, v68, v69 offset0:64 offset1:96
	v_mul_f32_e32 v68, v11, v74
	v_mul_f32_e32 v69, v59, v74
	ds_write2_b32 v73, v68, v69 offset0:128 offset1:160
	v_mul_f32_e32 v68, v43, v74
	v_mul_f32_e32 v69, v27, v74
	ds_write2_b32 v73, v68, v69 offset0:192 offset1:224
	v_mul_f32_e32 v68, v12, v72
	v_mul_f32_e32 v69, v60, v72
	v_add_u32_e32 v73, 0x3000, v65
	ds_write2_b32 v73, v68, v69 offset1:32
	v_mul_f32_e32 v68, v44, v72
	v_mul_f32_e32 v69, v28, v72
	ds_write2_b32 v73, v68, v69 offset0:64 offset1:96
	v_mul_f32_e32 v68, v13, v70
	v_mul_f32_e32 v69, v61, v70
	ds_write2_b32 v73, v68, v69 offset0:128 offset1:160
	v_mul_f32_e32 v68, v45, v70
	v_mul_f32_e32 v69, v29, v70
	ds_write2_b32 v73, v68, v69 offset0:192 offset1:224
	v_mul_f32_e32 v68, v14, v66
	v_mul_f32_e32 v69, v62, v66
	v_add_u32_e32 v65, 0x3400, v65
	ds_write2_b32 v65, v68, v69 offset1:32
	v_mul_f32_e32 v68, v46, v66
	v_mul_f32_e32 v69, v30, v66
	ds_write2_b32 v65, v68, v69 offset0:64 offset1:96
	v_mul_f32_e32 v68, v15, v64
	v_mul_f32_e32 v69, v63, v64
	ds_write2_b32 v65, v68, v69 offset0:128 offset1:160
	v_mul_f32_e32 v68, v47, v64
	v_mul_f32_e32 v69, v31, v64
	ds_write2_b32 v65, v68, v69 offset0:192 offset1:224

.LBB0_805:
	s_lshl_b32 s0, s39, 10
	s_and_b32 s6, s0, 0x800000
	s_lshl_b32 s0, s43, 1
	s_and_b32 s65, s0, 0x300
	s_lshl_b32 s0, s2, 11
	s_lshl_b32 s1, s2, 4
	s_and_b32 s0, s0, 0x2000
	s_and_b32 s1, s1, 0xffffff80
	s_add_i32 s1, s0, s1
	v_or_b32_e32 v171, s1, v170
	v_or_b32_e32 v0, v171, v169
	v_ashrrev_i32_e32 v1, 31, v0
	s_lshl_b32 s1, s2, 7
	v_lshlrev_b64 v[0:1], 10, v[0:1]
	s_and_b32 s64, s1, 0x180
	v_lshl_add_u64 v[0:1], s[86:87], 0, v[0:1]
	s_lshl_b32 s4, s64, 1
	s_mov_b32 s5, s7
	v_lshl_add_u64 v[0:1], v[0:1], 0, s[4:5]
	s_lshl_b32 s5, s0, 10
	s_add_u32 s0, s33, s5
	s_addc_u32 s1, s34, 0
	s_add_u32 s0, s0, s4
	v_mov_b32_e32 v174, v168
	v_lshl_add_u64 v[0:1], v[160:161], 1, v[0:1]
	s_addc_u32 s1, s1, 0
	v_lshl_add_u64 v[0:1], v[0:1], 0, v[162:163]
	v_ashrrev_i32_e32 v16, 4, v174
	s_add_u32 s5, s35, s5
	v_lshlrev_b32_e32 v20, 3, v174
	v_add_u32_e32 v18, 32, v16
	s_addc_u32 s16, s38, 0
	global_load_dwordx4 v[124:127], v[0:1], off
	global_load_dwordx4 v[120:123], v[0:1], off offset:32
	global_load_dwordx4 v[116:119], v[0:1], off offset:64
	global_load_dwordx4 v[112:115], v[0:1], off offset:96
	v_and_b32_e32 v0, 0x78, v20
	v_ashrrev_i32_e32 v17, 31, v16
	v_ashrrev_i32_e32 v19, 31, v18
	s_add_u32 s4, s5, s4
	v_lshlrev_b32_e32 v21, 1, v0
	v_lshlrev_b64 v[48:49], 10, v[16:17]
	v_lshlrev_b64 v[12:13], 10, v[18:19]
	s_addc_u32 s5, s16, 0
	v_or_b32_e32 v50, v48, v21
	v_mov_b32_e32 v51, v49
	v_or_b32_e32 v12, v12, v21
	v_lshl_add_u64 v[0:1], s[4:5], 0, v[50:51]
	v_lshl_add_u64 v[4:5], s[4:5], 0, v[12:13]
	s_barrier
	global_load_dwordx4 v[0:3], v[0:1], off
	s_nop 0
	global_load_dwordx4 v[4:7], v[4:5], off
	v_lshl_add_u64 v[8:9], s[0:1], 0, v[50:51]
	global_load_dwordx4 v[8:11], v[8:9], off
	v_lshl_add_u64 v[12:13], s[0:1], 0, v[12:13]
	global_load_dwordx4 v[12:15], v[12:13], off
	v_and_b32_e32 v22, 0xfffff0, v16
	v_lshlrev_b32_e32 v23, 1, v16
	v_lshrrev_b32_e32 v24, 1, v16
	v_and_b32_e32 v25, 3, v16
	v_and_or_b32 v22, v23, 8, v22
	v_and_or_b32 v23, v24, 4, v25
	v_and_b32_e32 v24, 0xfffff0, v18
	v_lshlrev_b32_e32 v25, 1, v18
	v_and_b32_e32 v17, 0x70, v174
	v_bfe_u32 v20, v20, 5, 2
	v_lshlrev_b32_e32 v16, 8, v16
	v_lshrrev_b32_e32 v22, 1, v22
	v_and_or_b32 v24, v25, 8, v24
	v_bitop3_b32 v183, v21, v16, v17 bitop3:0xde
	v_or_b32_e32 v16, v22, v20
	v_lshrrev_b32_e32 v22, 1, v24
	v_lshlrev_b32_e32 v23, 6, v23
	v_and_b32_e32 v26, 48, v21
	v_lshlrev_b32_e32 v16, 9, v16
	v_or_b32_e32 v20, v22, v20
	v_or3_b32 v184, v16, v23, v26
	v_lshlrev_b32_e32 v16, 9, v20
	v_bfe_u32 v172, v174, 5, 1
	v_ashrrev_i32_e32 v175, 8, v174
	v_lshlrev_b32_e32 v52, 4, v174
	v_or3_b32 v186, v16, v23, v26
	v_add_u32_e32 v84, 16, v184
	v_and_b32_e32 v173, 31, v174
	v_lshlrev_b32_e32 v19, 7, v175
	v_add_u32_e32 v24, 16, v183
	v_add_u32_e32 v85, 16, v186
	s_waitcnt vmcnt(0)
	v_lshlrev_b32_e32 v176, 4, v172
	v_lshlrev_b32_e32 v190, 8, v173
	v_and_b32_e32 v86, 63, v174
	v_lshl_add_u64 v[60:61], v[50:51], 0, s[14:15]
	v_lshl_add_u64 v[64:65], v[50:51], 0, s[36:37]
	v_lshl_add_u64 v[56:57], s[4:5], 0, v[64:65]
	v_lshl_add_u64 v[64:65], s[0:1], 0, v[64:65]
	s_cmp_lg_u32 16, -1
	s_cselect_b32 s16, 16, 0
	s_mov_b32 s17, s7
	s_mov_b32 s18, s7
	s_mov_b32 s19, s7
	s_mov_b32 s20, s7
	s_waitcnt vmcnt(3)
	ds_write_b128 v84, v[0:3]
	s_waitcnt vmcnt(2)
	ds_write_b128 v85, v[4:7]
	s_waitcnt vmcnt(1)
	ds_write_b128 v24, v[8:11] offset:49152
	v_and_b32_e32 v8, 0x70, v52
	v_lshlrev_b32_e32 v0, 8, v18
	v_bitop3_b32 v182, v176, v8, v19 bitop3:0x36
	v_bitop3_b32 v188, v21, v0, v17 bitop3:0xde
	v_add_u32_e32 v185, v182, v190
	v_add_u32_e32 v0, 16, v188
	v_add_u32_e32 v4, 16, v185
	s_waitcnt vmcnt(0)
	ds_write_b128 v0, v[12:15] offset:49152
	s_waitcnt lgkmcnt(0)
	s_barrier
	ds_read_b128 v[0:3], v4 offset:49152
	ds_read_b128 v[4:7], v4 offset:57344
	v_or_b32_e32 v9, v176, v19
	v_bitop3_b32 v187, v9, v8, 32 bitop3:0x36
	v_add_u32_e32 v189, v187, v190
	s_waitcnt lgkmcnt(0)
	v_mfma_f32_32x32x16_bf16 v[16:31], v[4:7], v[124:127], 0
	v_add_u32_e32 v4, 16, v189
	v_bitop3_b32 v193, v9, v8, s3 bitop3:0x36
	v_bitop3_b32 v191, v9, v8, 64 bitop3:0x36
	v_add_u32_e32 v194, v193, v190
	v_add_u32_e32 v192, v191, v190
	v_add_u32_e32 v8, 16, v194
	v_and_b32_e32 v5, 0x3fffffc0, v174
	v_mfma_f32_32x32x16_bf16 v[32:47], v[0:3], v[124:127], 0
	ds_read_b128 v[0:3], v4 offset:49152
	v_and_b32_e32 v11, 0xc0, v52
	v_add_u32_e32 v13, 16, v192
	ds_read_b128 v[52:55], v8 offset:57344
	v_lshl_add_u32 v177, v5, 2, s50
	ds_read_b128 v[4:7], v4 offset:57344
	v_lshlrev_b32_e32 v10, 3, v86
	s_waitcnt lgkmcnt(2)
	v_mfma_f32_32x32x16_bf16 v[32:47], v[0:3], v[120:123], v[32:47]
	v_lshlrev_b32_e32 v0, 1, v174
	v_and_b32_e32 v12, 32, v0
	ds_read_b128 v[0:3], v13 offset:49152
	v_and_or_b32 v11, v10, 24, v11
	s_mov_b32 s21, s7
	s_mov_b32 s22, s7
	s_mov_b32 s23, s7
	s_waitcnt lgkmcnt(0)
	v_mfma_f32_32x32x16_bf16 v[32:47], v[0:3], v[116:119], v[32:47]
	ds_read_b128 v[0:3], v8 offset:49152
	s_mov_b32 s24, s7
	s_mov_b32 s25, s7
	s_mov_b32 s26, s7
	s_mov_b32 s27, s7
	s_mov_b32 s28, s7
	s_mov_b32 s29, s7
	v_mfma_f32_32x32x16_bf16 v[16:31], v[4:7], v[120:123], v[16:31]
	v_and_b32_e32 v4, 0x100, v10
	v_lshlrev_b32_e32 v4, 3, v4
	v_or3_b32 v178, v11, v12, v4
	ds_read_b128 v[4:7], v13 offset:57344
	v_add_u32_e32 v181, s16, v178
	s_mov_b32 s16, s7
	s_mov_b32 s30, s7
	s_mov_b32 s31, s7
	s_waitcnt lgkmcnt(0)
	v_mfma_f32_32x32x16_bf16 v[16:31], v[4:7], v[116:119], v[16:31]
	v_lshl_add_u32 v179, v173, 2, v177
	v_mov_b32_e32 v196, 1.0
	v_mov_b32_e32 v180, 0
	v_mfma_f32_32x32x16_bf16 v[32:47], v[0:3], v[112:115], v[32:47]
	v_mov_b64_e32 v[0:1], s[16:17]
	v_mov_b64_e32 v[14:15], s[30:31]
	v_mov_b64_e32 v[2:3], s[18:19]
	v_mov_b64_e32 v[4:5], s[20:21]
	v_mov_b64_e32 v[6:7], s[22:23]
	v_mov_b64_e32 v[8:9], s[24:25]
	v_mov_b64_e32 v[10:11], s[26:27]
	v_mfma_f32_32x32x16_bf16 v[16:31], v[52:55], v[112:115], v[16:31]
	s_nop 3
	v_max_f32_e32 v52, v33, v33
	v_max_f32_e32 v53, v32, v32
	v_max_f32_e32 v52, v53, v52
	v_max3_f32 v52, v52, v34, v35
	v_max3_f32 v52, v52, v36, v37
	v_max3_f32 v52, v52, v38, v39
	v_max3_f32 v52, v52, v40, v41
	v_max3_f32 v52, v52, v42, v43
	v_max3_f32 v52, v52, v44, v45
	v_max3_f32 v66, v52, v46, v47
	v_lshl_add_u64 v[52:53], s[4:5], 0, v[60:61]
	v_lshl_add_u64 v[60:61], s[0:1], 0, v[60:61]
	global_load_dwordx4 v[52:55], v[52:53], off
	s_nop 0
	global_load_dwordx4 v[56:59], v[56:57], off
	v_mov_b64_e32 v[12:13], s[28:29]
	global_load_dwordx4 v[60:63], v[60:61], off
	s_mov_b32 s19, 1
	global_load_dwordx4 v[80:83], v[64:65], off
	v_max3_f32 v64, v66, v16, v17
	v_max3_f32 v64, v64, v18, v19
	v_max3_f32 v64, v64, v20, v21
	v_max3_f32 v64, v64, v22, v23
	v_max3_f32 v64, v64, v24, v25
	v_max3_f32 v64, v64, v26, v27
	v_max3_f32 v64, v64, v28, v29
	v_max3_f32 v70, v64, v30, v31
	v_lshl_add_u64 v[64:65], v[50:51], 0, s[40:41]
	v_lshl_add_u64 v[66:67], s[0:1], 0, v[64:65]
	v_lshl_add_u64 v[50:51], v[50:51], 0, s[44:45]
	v_lshl_add_u64 v[64:65], s[4:5], 0, v[64:65]
	v_lshl_add_u64 v[68:69], s[0:1], 0, v[50:51]
	global_load_dwordx4 v[136:139], v[66:67], off
	global_load_dwordx4 v[128:131], v[68:69], off
	v_lshl_add_u64 v[50:51], s[4:5], 0, v[50:51]
	global_load_dwordx4 v[140:143], v[64:65], off
	global_load_dwordx4 v[132:135], v[50:51], off
	v_mov_b32_e32 v71, v70
	s_nop 1
	v_permlane32_swap_b32_e32 v70, v71
	v_max_f32_e32 v50, v71, v71
	v_max_f32_e32 v51, v70, v70
	v_max_f32_e32 v50, v51, v50
	v_sub_f32_e32 v64, v16, v50
	v_add_u32_e32 v16, s58, v183
	v_sub_f32_e32 v32, v32, v50
	v_sub_f32_e32 v33, v33, v50
	v_sub_f32_e32 v34, v34, v50
	v_sub_f32_e32 v35, v35, v50
	v_sub_f32_e32 v36, v36, v50
	v_sub_f32_e32 v37, v37, v50
	v_sub_f32_e32 v38, v38, v50
	v_sub_f32_e32 v39, v39, v50
	v_sub_f32_e32 v40, v40, v50
	v_sub_f32_e32 v41, v41, v50
	v_sub_f32_e32 v42, v42, v50
	v_sub_f32_e32 v43, v43, v50
	v_sub_f32_e32 v44, v44, v50
	v_sub_f32_e32 v45, v45, v50
	v_sub_f32_e32 v46, v46, v50
	v_sub_f32_e32 v47, v47, v50
	v_sub_f32_e32 v66, v18, v50
	s_waitcnt vmcnt(4)
	s_waitcnt vmcnt(7)
	ds_write_b128 v84, v[52:55] offset:16384
	s_waitcnt vmcnt(6)
	ds_write_b128 v85, v[56:59] offset:16384
	v_and_b32_e32 v18, 15, v174
	s_waitcnt vmcnt(5)
	ds_write_b128 v16, v[60:63]
	v_add_u32_e32 v16, s58, v188
	v_sub_f32_e32 v65, v17, v50
	v_exp_f32_e32 v152, v32
	v_exp_f32_e32 v153, v33
	v_exp_f32_e32 v154, v34
	v_exp_f32_e32 v155, v35
	v_exp_f32_e32 v156, v36
	v_exp_f32_e32 v157, v37
	v_exp_f32_e32 v158, v38
	v_exp_f32_e32 v159, v39
	v_exp_f32_e32 v144, v40
	v_exp_f32_e32 v145, v41
	v_exp_f32_e32 v146, v42
	v_exp_f32_e32 v147, v43
	v_exp_f32_e32 v148, v44
	v_exp_f32_e32 v149, v45
	v_exp_f32_e32 v150, v46
	v_exp_f32_e32 v151, v47
	s_waitcnt vmcnt(4)
	ds_write_b128 v16, v[80:83]
	v_lshl_add_u64 v[16:17], s[6:7], 0, v[48:49]
	v_lshlrev_b32_e32 v18, 4, v18
	v_or3_b32 v16, v16, s65, v18
	v_add_f32_e32 v195, 0, v50
	v_sub_f32_e32 v79, v31, v50
	v_sub_f32_e32 v78, v30, v50
	v_sub_f32_e32 v77, v29, v50
	v_sub_f32_e32 v76, v28, v50
	v_sub_f32_e32 v75, v27, v50
	v_sub_f32_e32 v74, v26, v50
	v_sub_f32_e32 v73, v25, v50
	v_sub_f32_e32 v72, v24, v50
	v_sub_f32_e32 v71, v23, v50
	v_sub_f32_e32 v70, v22, v50
	v_sub_f32_e32 v69, v21, v50
	v_sub_f32_e32 v68, v20, v50
	v_sub_f32_e32 v67, v19, v50
	v_lshl_add_u64 v[166:167], s[12:13], 0, v[16:17]
	v_mov_b64_e32 v[62:63], v[14:15]
	v_mov_b64_e32 v[46:47], v[14:15]
	v_mov_b64_e32 v[30:31], v[14:15]
	v_cmp_gt_u32_e64 s[0:1], 32, v86
	v_mov_b64_e32 v[60:61], v[12:13]
	v_mov_b64_e32 v[58:59], v[10:11]
	v_mov_b64_e32 v[56:57], v[8:9]
	v_mov_b64_e32 v[54:55], v[6:7]
	v_mov_b64_e32 v[52:53], v[4:5]
	v_mov_b64_e32 v[50:51], v[2:3]
	v_mov_b64_e32 v[48:49], v[0:1]
	v_mov_b64_e32 v[44:45], v[12:13]
	v_mov_b64_e32 v[42:43], v[10:11]
	v_mov_b64_e32 v[40:41], v[8:9]
	v_mov_b64_e32 v[38:39], v[6:7]
	v_mov_b64_e32 v[36:37], v[4:5]
	v_mov_b64_e32 v[34:35], v[2:3]
	v_mov_b64_e32 v[32:33], v[0:1]
	v_mov_b64_e32 v[28:29], v[12:13]
	v_mov_b64_e32 v[26:27], v[10:11]
	v_mov_b64_e32 v[24:25], v[8:9]
	v_mov_b64_e32 v[22:23], v[6:7]
	v_mov_b64_e32 v[20:21], v[4:5]
	v_mov_b64_e32 v[18:19], v[2:3]
	v_mov_b64_e32 v[16:17], v[0:1]
	s_mov_b32 s6, 1
	s_mov_b32 s18, 0
	s_waitcnt lgkmcnt(0)
	s_barrier
	v_add_co_u32_e32 v242, vcc, s61, v166
	s_nop 1
	v_addc_co_u32_e32 v243, vcc, -1, v167, vcc
	s_nop 0
	v_readfirstlane_b32 s98, v242
	v_readfirstlane_b32 s99, v243
	s_nop 1
	v_subrev_u32_e32 v242, s98, v242
	v_add_u32_e32 v243, 0x8000, v242
	v_add_u32_e32 v244, 0x1000000, v242
	v_add_u32_e32 v245, 0x1008000, v242
